# P0: rotate the x-row assignment by half the wave range so the 5th row trip lands on waves with only one weight-conversion item
# speedup vs baseline: 1.0040x; 1.0007x over previous
; __device__ __forceinline__ unsigned cvtpk(float lo, float hi) { f32x2_t v = {lo, hi}; bf16x2_t b = __builtin_convertvector(v, bf16x2_t); return __builtin_bit_cast(unsigned, b); }
; __global__ void __launch_bounds__(NTHREADS, 2) fwd_kernel(Params P) {
;     ...
;             f32x4 v[2][4], vn[2][4];
;             auto xrow = [&](int m) -> const f32x4* { const float* xr = (m < MP) ? P.in[0] + (size_t)m * D : P.in[1] + (size_t)(m - MP) * D; return (const f32x4*)xr + lane; };
;             int m0 = 2 * gw;
;             if (m0 < M) {
; #pragma unroll
;                 for (int q = 0; q < 2; ++q) { const f32x4* xv = xrow(m0 + q);
; #pragma unroll
;                     for (int j = 0; j < 4; ++j) v[q][j] = xv[64 * j]; }
;             }
;             for (; m0 < M; m0 += 2 * NGW) {
;                 const int mn = m0 + 2 * NGW; const bool more = mn < M;
;                 if (more) {
; #pragma unroll
;                     for (int q = 0; q < 2; ++q) { const f32x4* xv = xrow(mn + q);
; #pragma unroll
;                         for (int j = 0; j < 4; ++j) vn[q][j] = xv[64 * j]; }
;                 }
;                 float sq[2];
; #pragma unroll
;                 for (int q = 0; q < 2; ++q) { float s2 = 0.f;
; #pragma unroll
;                     for (int j = 0; j < 4; ++j) s2 += (v[q][j][0] * v[q][j][0] + v[q][j][1] * v[q][j][1]) + (v[q][j][2] * v[q][j][2] + v[q][j][3] * v[q][j][3]);
;                     sq[q] = wave_sum(s2); }
; #pragma unroll
;                 for (int q = 0; q < 2; ++q) { const int m = m0 + q; u32x2* o8 = (u32x2*)(XA + (size_t)m * D) + lane;
; #pragma unroll
;                     for (int j = 0; j < 4; ++j) o8[64 * j] = (u32x2){cvtpk(v[q][j][0], v[q][j][1]), cvtpk(v[q][j][2], v[q][j][3])};
;                     if (lane == 0) ssq0[(size_t)m * 16] = __builtin_amdgcn_rsqf(sq[q] * (1.0f / D) + EPS); }
.LBB0_251:
	s_xor_b32 s99, s70, 0x400
	v_readlane_b32 s78, v252, 14
	s_cmpk_gt_i32 s99, 0x207f
	v_readlane_b32 s79, v252, 15
	s_cbranch_scc1 .LBB0_262
	s_lshl_b32 s6, s99, 1
	s_add_i32 s0, s6, 0xffffc000
	s_ashr_i32 s7, s6, 31
	s_cmpk_lt_i32 s99, 0x2000
	s_cselect_b32 s1, s7, 0
	s_cselect_b32 s0, s6, s0
	s_cselect_b32 s3, s9, s11
	s_cselect_b32 s18, s8, s10
	s_lshl_b64 s[0:1], s[0:1], 12
	s_add_u32 s0, s18, s0
	s_addc_u32 s1, s3, s1
	s_waitcnt vmcnt(6)
	v_lshlrev_b32_e32 v30, 4, v198
	global_load_dwordx4 v[2:5], v30, s[0:1] nt
	global_load_dwordx4 v[6:9], v30, s[0:1] offset:1024 nt
	global_load_dwordx4 v[10:13], v30, s[0:1] offset:2048 nt
	global_load_dwordx4 v[14:17], v30, s[0:1] offset:3072 nt
	s_or_b32 s0, s6, 1
	s_add_i32 s3, s6, 0xffffc001
	s_ashr_i32 s1, s0, 31
	s_cmpk_lt_i32 s0, 0x4000
	s_cselect_b32 s1, s1, 0
	s_cselect_b32 s0, s0, s3
	s_cselect_b32 s3, s9, s11
	s_cselect_b32 s18, s8, s10
	s_lshl_b64 s[0:1], s[0:1], 12
	s_add_u32 s0, s18, s0
	s_addc_u32 s1, s3, s1
	global_load_dwordx4 v[18:21], v30, s[0:1] nt
	global_load_dwordx4 v[22:25], v30, s[0:1] offset:1024 nt
	global_load_dwordx4 v[26:29], v30, s[0:1] offset:2048 nt
	s_nop 0
	global_load_dwordx4 v[30:33], v30, s[0:1] offset:3072 nt
	s_waitcnt vmcnt(13)
	v_mbcnt_lo_u32_b32 v34, -1, 0
	v_mbcnt_hi_u32_b32 v34, -1, v34
	v_and_b32_e32 v35, 64, v34
	v_add_u32_e32 v35, 64, v35
	v_xor_b32_e32 v36, 1, v34
	v_cmp_lt_i32_e32 vcc, v36, v35
	s_lshl_b32 s18, s71, 4
	s_lshl_b64 s[20:21], s[6:7], 6
	v_cndmask_b32_e32 v36, v34, v36, vcc
	s_waitcnt vmcnt(10)
	v_lshlrev_b32_e32 v70, 2, v36
	v_xor_b32_e32 v36, 2, v34
	v_cmp_lt_i32_e32 vcc, v36, v35
	s_lshl_b64 s[24:25], s[6:7], 11
	s_lshl_b32 s3, s2, 4
	v_cndmask_b32_e32 v36, v34, v36, vcc
	v_lshlrev_b32_e32 v71, 2, v36
	v_xor_b32_e32 v36, 4, v34
	v_cmp_lt_i32_e32 vcc, v36, v35
	v_readlane_b32 s7, v252, 11
	s_add_i32 s3, s3, s18
	v_cndmask_b32_e32 v36, v34, v36, vcc
	v_lshlrev_b32_e32 v72, 2, v36
	v_xor_b32_e32 v36, 8, v34
	v_cmp_lt_i32_e32 vcc, v36, v35
	s_lshl_b32 s7, s7, 1
	s_ashr_i32 s19, s18, 31
	v_cndmask_b32_e32 v36, v34, v36, vcc
	v_lshlrev_b32_e32 v73, 2, v36
	v_xor_b32_e32 v36, 16, v34
	v_cmp_lt_i32_e32 vcc, v36, v35
	s_add_i32 s3, s3, s7
	s_xor_b32 s3, s3, 0x800
	v_cmp_eq_u32_e64 s[0:1], 0, v198
	v_cndmask_b32_e32 v36, v34, v36, vcc
	s_waitcnt vmcnt(9)
	v_lshlrev_b32_e32 v74, 2, v36
	v_xor_b32_e32 v36, 32, v34
	v_cmp_lt_i32_e32 vcc, v36, v35
	s_lshl_b64 s[28:29], s[18:19], 6
	v_lshl_or_b32 v66, v198, 3, s24
	v_cndmask_b32_e32 v34, v34, v36, vcc
	v_lshlrev_b32_e32 v75, 2, v34
	v_mov_b32_e32 v67, s25
	s_lshl_b64 s[30:31], s[18:19], 11
	s_ashr_i32 s7, s3, 31
	v_lshlrev_b32_e32 v76, 4, v198
	s_mov_b32 s24, 0x580000
	v_mov_b32_e32 v77, 0x358637bd
	s_waitcnt vmcnt(8)
	v_mov_b32_e32 v78, 0x10000
	s_branch .LBB0_254
